# baseline (speedup 1.0000x reference)
; __device__ __forceinline__ void gla_load_vT(unsigned char* lds, const bf16_t* P, int row0, int nvalid, int colbase, const bf16_t* vtsrc) {
;     ...
;     const bf16_t* vp = P + (size_t)(row0 + th * 32) * NPROJ + colbase;
;     unsigned w[16];
; #pragma unroll
;     for (int i2 = 0; i2 < 16; ++i2) { const int t0 = th * 32 + 2 * i2;
;         unsigned lo = 0u, hi = 0u;
;         if (t0 < nvalid) { lo = vp[(2 * i2) * NPROJ + vd]; hi = vp[(2 * i2 + 1) * NPROJ + vd]; }
;         w[i2] = lo | (hi << 16); }
.LBB0_1003:
	s_andn2_b64 vcc, exec, s[12:13]
	s_cbranch_vccnz .LBB0_1023
	s_add_i32 s0, s14, s75
	s_mul_hi_i32 s1, s0, 0x3200
	s_mulk_i32 s0, 0x3200
	v_readlane_b32 s12, v251, 50
	v_readlane_b32 s13, v251, 51
	s_add_u32 s0, s12, s0
	s_addc_u32 s1, s13, s1
	s_lshl_b32 s12, s16, 1
	s_add_u32 s0, s0, s12
	s_addc_u32 s1, s1, 0
	s_add_u32 s0, s0, 0x1000
	s_addc_u32 s1, s1, 0
	s_sub_i32 s12, s84, s14
	v_mov_b32_e32 v1, 0
	s_cmp_lt_i32 s12, 1
	v_lshlrev_b32_e32 v36, 1, v0
	v_mov_b32_e32 v0, 0
	s_cbranch_scc1 .Lmy_glac_vt_skip
	s_mov_b32 s98, s0
	s_mov_b32 s99, s1
	global_load_ushort v200, v36, s[98:99]
	s_add_u32 s98, s98, 0x3200
	s_addc_u32 s99, s99, 0
	global_load_ushort v201, v36, s[98:99]
	s_add_u32 s98, s98, 0x3200
	s_addc_u32 s99, s99, 0
	global_load_ushort v202, v36, s[98:99]
	s_add_u32 s98, s98, 0x3200
	s_addc_u32 s99, s99, 0
	global_load_ushort v203, v36, s[98:99]
	s_add_u32 s98, s98, 0x3200
	s_addc_u32 s99, s99, 0
	global_load_ushort v204, v36, s[98:99]
	s_add_u32 s98, s98, 0x3200
	s_addc_u32 s99, s99, 0
	global_load_ushort v205, v36, s[98:99]
	s_add_u32 s98, s98, 0x3200
	s_addc_u32 s99, s99, 0
	global_load_ushort v206, v36, s[98:99]
	s_add_u32 s98, s98, 0x3200
	s_addc_u32 s99, s99, 0
	global_load_ushort v207, v36, s[98:99]
	s_add_u32 s98, s98, 0x3200
	s_addc_u32 s99, s99, 0
	global_load_ushort v200, v36, s[98:99]
	s_add_u32 s98, s98, 0x3200
	s_addc_u32 s99, s99, 0
	global_load_ushort v201, v36, s[98:99]
	s_add_u32 s98, s98, 0x3200
	s_addc_u32 s99, s99, 0
	global_load_ushort v202, v36, s[98:99]
	s_add_u32 s98, s98, 0x3200
	s_addc_u32 s99, s99, 0
	global_load_ushort v203, v36, s[98:99]
	s_add_u32 s98, s98, 0x3200
	s_addc_u32 s99, s99, 0
	global_load_ushort v204, v36, s[98:99]
	s_add_u32 s98, s98, 0x3200
	s_addc_u32 s99, s99, 0
	global_load_ushort v205, v36, s[98:99]
	s_add_u32 s98, s98, 0x3200
	s_addc_u32 s99, s99, 0
	global_load_ushort v206, v36, s[98:99]
	s_add_u32 s98, s98, 0x3200
	s_addc_u32 s99, s99, 0
	global_load_ushort v207, v36, s[98:99]
	s_add_u32 s98, s98, 0x3200
	s_addc_u32 s99, s99, 0
	global_load_ushort v200, v36, s[98:99]
	s_add_u32 s98, s98, 0x3200
	s_addc_u32 s99, s99, 0
	global_load_ushort v201, v36, s[98:99]
	s_add_u32 s98, s98, 0x3200
	s_addc_u32 s99, s99, 0
	global_load_ushort v202, v36, s[98:99]
	s_add_u32 s98, s98, 0x3200
	s_addc_u32 s99, s99, 0
	global_load_ushort v203, v36, s[98:99]
	s_add_u32 s98, s98, 0x3200
	s_addc_u32 s99, s99, 0
	global_load_ushort v204, v36, s[98:99]
	s_add_u32 s98, s98, 0x3200
	s_addc_u32 s99, s99, 0
	global_load_ushort v205, v36, s[98:99]
	s_add_u32 s98, s98, 0x3200
	s_addc_u32 s99, s99, 0
	global_load_ushort v206, v36, s[98:99]
	s_add_u32 s98, s98, 0x3200
	s_addc_u32 s99, s99, 0
	global_load_ushort v207, v36, s[98:99]
	s_add_u32 s98, s98, 0x3200
	s_addc_u32 s99, s99, 0
	global_load_ushort v200, v36, s[98:99]
	s_add_u32 s98, s98, 0x3200
	s_addc_u32 s99, s99, 0
	global_load_ushort v201, v36, s[98:99]
	s_add_u32 s98, s98, 0x3200
	s_addc_u32 s99, s99, 0
	global_load_ushort v202, v36, s[98:99]
	s_add_u32 s98, s98, 0x3200
	s_addc_u32 s99, s99, 0
	global_load_ushort v203, v36, s[98:99]
	s_add_u32 s98, s98, 0x3200
	s_addc_u32 s99, s99, 0
	global_load_ushort v204, v36, s[98:99]
	s_add_u32 s98, s98, 0x3200
	s_addc_u32 s99, s99, 0
	global_load_ushort v205, v36, s[98:99]
	s_add_u32 s98, s98, 0x3200
	s_addc_u32 s99, s99, 0
	global_load_ushort v206, v36, s[98:99]
	s_add_u32 s98, s98, 0x3200
	s_addc_u32 s99, s99, 0
	global_load_ushort v207, v36, s[98:99]
.Lmy_glac_vt_skip:
	s_cmp_lt_i32 s12, 1
	s_cbranch_scc1 .LBB0_1006
	v_lshl_add_u64 v[2:3], s[0:1], 0, v[36:37]
	v_add_co_u32_e32 v2, vcc, 0x3000, v2
	s_nop 1
	v_addc_co_u32_e32 v3, vcc, 0, v3, vcc
	global_load_ushort v0, v36, s[0:1]
	s_nop 0
	global_load_ushort v2, v[2:3], off offset:512
	s_waitcnt vmcnt(0)
	v_lshl_or_b32 v0, v2, 16, v0

; __device__ __forceinline__ f32x4 mfma16(bf16x8 a, bf16x8 b, f32x4 c) { return __builtin_amdgcn_mfma_f32_16x16x32_bf16(a, b, c, 0, 0, 0); }
; __device__ __forceinline__ void spatial_phase(unsigned char* lds, const Params& p, int vb, int G, bool dry) {
;     ...
;         for (int ks = 0; ks < 4; ++ks) { bf16x8 af[2];
; #pragma unroll
;             for (int v = 0; v < 2; ++v) af[v] = *(const bf16x8*)(vTl + (16 * (2 * wave + v) + li) * 136 + 32 * ks + 8 * fq);
; #pragma unroll
;             for (int tb = 0; tb < 8; ++tb) { const bf16x8 bf_ = *(const bf16x8*)(Wl + (16 * tb + li) * 136 + 32 * ks + 8 * fq); acc[0][tb] = mfma16(af[0], bf_, acc[0][tb]); acc[1][tb] = mfma16(af[1], bf_, acc[1][tb]); } }
;     ...
;                 for (int v = 0; v < 2; ++v) { bf16_t* up = U + (size_t)(row0 + t) * D + g * 256 + 16 * (2 * wave + v) + 4 * fq; const u32x2 uw = *(const u32x2*)up;
.LBB0_1586:
.LBB0_1587:
	s_waitcnt lgkmcnt(0)
	s_barrier
	ds_read_b128 v[34:37], v161 offset:34816
	ds_read_b128 v[38:41], v161 offset:39168
	ds_read_b128 v[42:45], v162
	ds_read_b128 v[50:53], v162 offset:4352
	ds_read_b128 v[58:61], v162 offset:8704
	ds_read_b128 v[66:69], v162 offset:13056
	ds_read_b128 v[74:77], v162 offset:17408
	ds_read_b128 v[82:85], v162 offset:21760
	ds_read_b128 v[90:93], v162 offset:26112
	ds_read_b128 v[168:171], v162 offset:30464
	s_waitcnt lgkmcnt(7)
	v_mfma_f32_16x16x32_bf16 v[46:49], v[34:37], v[42:45], 0
	s_lshl_b32 s4, s58, 9
	s_and_b32 s20, s4, 0xe00
	v_lshl_add_u64 v[132:133], v[128:129], 0, s[20:21]
	v_mfma_f32_16x16x32_bf16 v[42:45], v[38:41], v[42:45], 0
	v_readlane_b32 s40, v251, 2
	s_lshl_b64 s[4:5], s[38:39], 1
	v_lshl_or_b32 v0, v134, 2, s20
	v_add_u32_e32 v200, s62, v134
	v_ashrrev_i32_e32 v201, 31, v200
	v_lshlrev_b64 v[200:201], 12, v[200:201]
	v_lshl_add_u64 v[200:201], v[132:133], 0, v[200:201]
	v_lshl_add_u64 v[200:201], v[200:201], 0, s[4:5]
	s_mov_b32 s98, 0x10000
	s_mov_b32 s99, 0
	global_load_dwordx2 v[214:215], v[200:201], off
	global_load_dwordx2 v[216:217], v[200:201], off offset:32
	v_lshl_add_u64 v[200:201], v[200:201], 0, s[98:99]
	global_load_dwordx2 v[218:219], v[200:201], off
	global_load_dwordx2 v[220:221], v[200:201], off offset:32
	v_lshl_add_u64 v[200:201], v[200:201], 0, s[98:99]
	global_load_dwordx2 v[222:223], v[200:201], off
	global_load_dwordx2 v[224:225], v[200:201], off offset:32
	v_lshl_add_u64 v[200:201], v[200:201], 0, s[98:99]
	global_load_dwordx2 v[226:227], v[200:201], off
	global_load_dwordx2 v[228:229], v[200:201], off offset:32
	v_lshl_add_u64 v[200:201], v[200:201], 0, s[98:99]
	global_load_dwordx2 v[230:231], v[200:201], off
	global_load_dwordx2 v[232:233], v[200:201], off offset:32
	v_lshl_add_u64 v[200:201], v[200:201], 0, s[98:99]
	global_load_dwordx2 v[234:235], v[200:201], off
	global_load_dwordx2 v[236:237], v[200:201], off offset:32
	v_lshl_add_u64 v[200:201], v[200:201], 0, s[98:99]
	global_load_dwordx2 v[238:239], v[200:201], off
	global_load_dwordx2 v[240:241], v[200:201], off offset:32
	v_lshl_add_u64 v[200:201], v[200:201], 0, s[98:99]
	global_load_dwordx2 v[242:243], v[200:201], off
	global_load_dwordx2 v[244:245], v[200:201], off offset:32
	s_waitcnt lgkmcnt(6)
	v_mfma_f32_16x16x32_bf16 v[54:57], v[34:37], v[50:53], 0
	v_readlane_b32 s41, v251, 3
	v_cmp_gt_u32_e32 vcc, s63, v145
	v_readlane_b32 s42, v251, 4
	v_mfma_f32_16x16x32_bf16 v[50:53], v[38:41], v[50:53], 0
	v_readlane_b32 s43, v251, 5
	v_readlane_b32 s44, v251, 6
	v_readlane_b32 s45, v251, 7
	s_waitcnt lgkmcnt(5)
	v_mfma_f32_16x16x32_bf16 v[62:65], v[34:37], v[58:61], 0
	v_readlane_b32 s46, v251, 8
	v_readlane_b32 s47, v251, 9
	v_readlane_b32 s48, v251, 10
	v_mfma_f32_16x16x32_bf16 v[58:61], v[38:41], v[58:61], 0
	v_readlane_b32 s49, v251, 11
	v_readlane_b32 s50, v251, 12
	v_readlane_b32 s51, v251, 13
	s_waitcnt lgkmcnt(4)
	v_mfma_f32_16x16x32_bf16 v[70:73], v[34:37], v[66:69], 0
	v_readlane_b32 s52, v251, 14
	v_readlane_b32 s53, v251, 15
	v_readlane_b32 s54, v251, 16
	v_mfma_f32_16x16x32_bf16 v[66:69], v[38:41], v[66:69], 0
	v_readlane_b32 s55, v251, 17
	s_waitcnt lgkmcnt(3)
	v_mfma_f32_16x16x32_bf16 v[78:81], v[34:37], v[74:77], 0
	v_mfma_f32_16x16x32_bf16 v[74:77], v[38:41], v[74:77], 0
	s_waitcnt lgkmcnt(2)
	v_mfma_f32_16x16x32_bf16 v[86:89], v[34:37], v[82:85], 0
	v_mfma_f32_16x16x32_bf16 v[82:85], v[38:41], v[82:85], 0
	s_waitcnt lgkmcnt(1)
	v_mfma_f32_16x16x32_bf16 v[164:167], v[34:37], v[90:93], 0
	v_mfma_f32_16x16x32_bf16 v[90:93], v[38:41], v[90:93], 0
	s_waitcnt lgkmcnt(0)
	v_mfma_f32_16x16x32_bf16 v[34:37], v[34:37], v[168:171], 0
	v_mfma_f32_16x16x32_bf16 v[38:41], v[38:41], v[168:171], 0
	ds_read_b128 v[168:171], v161 offset:34880
	ds_read_b128 v[172:175], v161 offset:39232
	ds_read_b128 v[176:179], v162 offset:64
	s_waitcnt lgkmcnt(0)
	v_mfma_f32_16x16x32_bf16 v[46:49], v[168:171], v[176:179], v[46:49]
	v_mfma_f32_16x16x32_bf16 v[42:45], v[172:175], v[176:179], v[42:45]
	ds_read_b128 v[176:179], v162 offset:4416
	s_waitcnt lgkmcnt(0)
	v_mfma_f32_16x16x32_bf16 v[54:57], v[168:171], v[176:179], v[54:57]
	v_mfma_f32_16x16x32_bf16 v[50:53], v[172:175], v[176:179], v[50:53]
	ds_read_b128 v[176:179], v162 offset:8768
	s_waitcnt lgkmcnt(0)
	v_mfma_f32_16x16x32_bf16 v[62:65], v[168:171], v[176:179], v[62:65]
	v_mfma_f32_16x16x32_bf16 v[58:61], v[172:175], v[176:179], v[58:61]
	ds_read_b128 v[176:179], v162 offset:13120
	s_waitcnt lgkmcnt(0)
	v_mfma_f32_16x16x32_bf16 v[70:73], v[168:171], v[176:179], v[70:73]
	v_mfma_f32_16x16x32_bf16 v[66:69], v[172:175], v[176:179], v[66:69]
	ds_read_b128 v[176:179], v162 offset:17472
	s_waitcnt lgkmcnt(0)
	v_mfma_f32_16x16x32_bf16 v[78:81], v[168:171], v[176:179], v[78:81]
	v_mfma_f32_16x16x32_bf16 v[74:77], v[172:175], v[176:179], v[74:77]
	ds_read_b128 v[176:179], v162 offset:21824
	s_waitcnt lgkmcnt(0)
	v_mfma_f32_16x16x32_bf16 v[86:89], v[168:171], v[176:179], v[86:89]
	v_mfma_f32_16x16x32_bf16 v[82:85], v[172:175], v[176:179], v[82:85]
	ds_read_b128 v[176:179], v162 offset:26176
	s_waitcnt lgkmcnt(0)
	v_mfma_f32_16x16x32_bf16 v[164:167], v[168:171], v[176:179], v[164:167]
	v_mfma_f32_16x16x32_bf16 v[90:93], v[172:175], v[176:179], v[90:93]
	ds_read_b128 v[176:179], v162 offset:30528
	s_waitcnt lgkmcnt(0)
	v_mfma_f32_16x16x32_bf16 v[34:37], v[168:171], v[176:179], v[34:37]
	v_mfma_f32_16x16x32_bf16 v[38:41], v[172:175], v[176:179], v[38:41]
	ds_read_b128 v[168:171], v161 offset:34944
	ds_read_b128 v[172:175], v161 offset:39296
	ds_read_b128 v[176:179], v162 offset:128
	s_waitcnt lgkmcnt(0)
; __device__ __forceinline__ unsigned cvt_pk(float lo, float hi) { unsigned r; asm("v_cvt_pk_bf16_f32 %0, %1, %2" : "=v"(r) : "v"(lo), "v"(hi)); return r; }
; __device__ __forceinline__ float bflo(unsigned w) { return __uint_as_float(w << 16); }
; __device__ __forceinline__ float bfhi(unsigned w) { return __uint_as_float(w & 0xffff0000u); }
; __device__ __forceinline__ f32x4 mfma16(bf16x8 a, bf16x8 b, f32x4 c) { return __builtin_amdgcn_mfma_f32_16x16x32_bf16(a, b, c, 0, 0, 0); }
; __device__ __forceinline__ void spatial_phase(unsigned char* lds, const Params& p, int vb, int G, bool dry) {
;     ...
;             for (int tb = 0; tb < 8; ++tb) { const bf16x8 bf_ = *(const bf16x8*)(Wl + (16 * tb + li) * 136 + 32 * ks + 8 * fq); acc[0][tb] = mfma16(af[0], bf_, acc[0][tb]); acc[1][tb] = mfma16(af[1], bf_, acc[1][tb]); } }
; #pragma unroll
;         for (int tb = 0; tb < 8; ++tb) { const int t = 16 * tb + li;
;             if (t < L && !dry) { const float bs = p.in[16][g * 128 + t];
; #pragma unroll
;                 for (int v = 0; v < 2; ++v) { bf16_t* up = U + (size_t)(row0 + t) * D + g * 256 + 16 * (2 * wave + v) + 4 * fq; const u32x2 uw = *(const u32x2*)up;
;                     u32x2 w; w.x = cvt_pk(bflo(uw.x) * (acc[v][tb][0] + bs), bfhi(uw.x) * (acc[v][tb][1] + bs)); w.y = cvt_pk(bflo(uw.y) * (acc[v][tb][2] + bs), bfhi(uw.y) * (acc[v][tb][3] + bs)); *(u32x2*)up = w; } } }
	v_mfma_f32_16x16x32_bf16 v[46:49], v[168:171], v[176:179], v[46:49]
	v_mfma_f32_16x16x32_bf16 v[42:45], v[172:175], v[176:179], v[42:45]
	ds_read_b128 v[176:179], v162 offset:4480
	s_waitcnt lgkmcnt(0)
	v_mfma_f32_16x16x32_bf16 v[54:57], v[168:171], v[176:179], v[54:57]
	v_mfma_f32_16x16x32_bf16 v[50:53], v[172:175], v[176:179], v[50:53]
	ds_read_b128 v[176:179], v162 offset:8832
	s_waitcnt lgkmcnt(0)
	v_mfma_f32_16x16x32_bf16 v[62:65], v[168:171], v[176:179], v[62:65]
	v_mfma_f32_16x16x32_bf16 v[58:61], v[172:175], v[176:179], v[58:61]
	ds_read_b128 v[176:179], v162 offset:13184
	s_waitcnt lgkmcnt(0)
	v_mfma_f32_16x16x32_bf16 v[70:73], v[168:171], v[176:179], v[70:73]
	v_mfma_f32_16x16x32_bf16 v[66:69], v[172:175], v[176:179], v[66:69]
	ds_read_b128 v[176:179], v162 offset:17536
	s_waitcnt lgkmcnt(0)
	v_mfma_f32_16x16x32_bf16 v[180:183], v[168:171], v[176:179], v[78:81]
	v_mfma_f32_16x16x32_bf16 v[176:179], v[172:175], v[176:179], v[74:77]
	s_nop 2
	ds_read_b128 v[74:77], v162 offset:21888
	s_waitcnt lgkmcnt(0)
	v_mfma_f32_16x16x32_bf16 v[184:187], v[168:171], v[74:77], v[86:89]
	v_mfma_f32_16x16x32_bf16 v[188:191], v[172:175], v[74:77], v[82:85]
	ds_read_b128 v[74:77], v162 offset:26240
	s_waitcnt lgkmcnt(0)
	v_mfma_f32_16x16x32_bf16 v[164:167], v[168:171], v[74:77], v[164:167]
	v_mfma_f32_16x16x32_bf16 v[192:195], v[172:175], v[74:77], v[90:93]
	ds_read_b128 v[74:77], v162 offset:30592
	s_waitcnt lgkmcnt(0)
	v_mfma_f32_16x16x32_bf16 v[34:37], v[168:171], v[74:77], v[34:37]
	v_mfma_f32_16x16x32_bf16 v[168:171], v[172:175], v[74:77], v[38:41]
	s_nop 2
	ds_read_b128 v[38:41], v161 offset:35008
	ds_read_b128 v[172:175], v161 offset:39360
	ds_read_b128 v[74:77], v162 offset:192
	global_load_dword v156, v0, s[40:41]
	s_waitcnt lgkmcnt(0)
	v_mfma_f32_16x16x32_bf16 v[90:93], v[172:175], v[74:77], v[42:45]
	s_nop 2
	ds_read_b128 v[42:45], v162 offset:4544
	s_waitcnt lgkmcnt(0)
	v_mfma_f32_16x16x32_bf16 v[86:89], v[38:41], v[42:45], v[54:57]
	s_waitcnt vmcnt(0)
	s_nop 0
	v_add_f32_e32 v90, v90, v156
	v_mfma_f32_16x16x32_bf16 v[82:85], v[172:175], v[42:45], v[50:53]
	ds_read_b128 v[42:45], v162 offset:8896
	v_add_f32_e32 v91, v91, v156
	v_add_f32_e32 v92, v92, v156
	v_mfma_f32_16x16x32_bf16 v[196:199], v[38:41], v[74:77], v[46:49]
	v_add_f32_e32 v93, v93, v156
	s_waitcnt lgkmcnt(0)
	v_mfma_f32_16x16x32_bf16 v[78:81], v[38:41], v[42:45], v[62:65]
	v_mfma_f32_16x16x32_bf16 v[74:77], v[172:175], v[42:45], v[58:61]
	ds_read_b128 v[42:45], v162 offset:13248
	s_nop 2
	v_add_f32_e32 v163, v196, v156
	s_waitcnt lgkmcnt(0)
	v_mfma_f32_16x16x32_bf16 v[70:73], v[38:41], v[42:45], v[70:73]
	v_mfma_f32_16x16x32_bf16 v[66:69], v[172:175], v[42:45], v[66:69]
	ds_read_b128 v[42:45], v162 offset:17600
	s_waitcnt lgkmcnt(0)
	v_mfma_f32_16x16x32_bf16 v[62:65], v[38:41], v[42:45], v[180:183]
	v_mfma_f32_16x16x32_bf16 v[58:61], v[172:175], v[42:45], v[176:179]
	ds_read_b128 v[42:45], v162 offset:21952
	s_waitcnt lgkmcnt(0)
	v_mfma_f32_16x16x32_bf16 v[54:57], v[38:41], v[42:45], v[184:187]
	v_mfma_f32_16x16x32_bf16 v[50:53], v[172:175], v[42:45], v[188:191]
	ds_read_b128 v[42:45], v162 offset:26304
	s_waitcnt lgkmcnt(0)
	v_mfma_f32_16x16x32_bf16 v[46:49], v[38:41], v[42:45], v[164:167]
	s_nop 2
	ds_read_b128 v[164:167], v162 offset:30656
	s_waitcnt lgkmcnt(0)
	v_mfma_f32_16x16x32_bf16 v[38:41], v[38:41], v[164:167], v[34:37]
	v_mfma_f32_16x16x32_bf16 v[34:37], v[172:175], v[164:167], v[168:171]
	v_add_u32_e32 v164, s62, v134
	v_ashrrev_i32_e32 v165, 31, v164
	v_lshlrev_b64 v[164:165], 12, v[164:165]
	v_lshl_add_u64 v[164:165], v[132:133], 0, v[164:165]
	v_lshl_add_u64 v[164:165], v[164:165], 0, s[4:5]
	global_load_dwordx2 v[166:167], v[164:165], off
	v_mfma_f32_16x16x32_bf16 v[42:45], v[172:175], v[42:45], v[192:195]
	s_waitcnt vmcnt(0)
	v_lshlrev_b32_e32 v157, 16, v166
	v_mul_f32_e32 v157, v163, v157
	v_and_b32_e32 v163, 0xffff0000, v166
	v_add_f32_e32 v166, v197, v156
	v_mul_f32_e32 v163, v166, v163
	v_cvt_pk_bf16_f32 v166, v157, v163
	v_lshlrev_b32_e32 v157, 16, v167
	v_add_f32_e32 v163, v198, v156
	v_mul_f32_e32 v157, v163, v157
	v_and_b32_e32 v163, 0xffff0000, v167
	v_add_f32_e32 v167, v199, v156
	v_mul_f32_e32 v163, v167, v163
	v_cvt_pk_bf16_f32 v167, v157, v163
	global_store_dwordx2 v[164:165], v[166:167], off
	global_load_dwordx2 v[166:167], v[164:165], off offset:32
	s_waitcnt vmcnt(0)
	v_lshlrev_b32_e32 v157, 16, v166
	v_mul_f32_e32 v90, v90, v157
	v_and_b32_e32 v157, 0xffff0000, v166
	v_mul_f32_e32 v91, v91, v157
	v_cvt_pk_bf16_f32 v90, v90, v91
	v_lshlrev_b32_e32 v91, 16, v167
	v_mul_f32_e32 v91, v92, v91
	v_and_b32_e32 v92, 0xffff0000, v167
	v_mul_f32_e32 v92, v93, v92
	v_cvt_pk_bf16_f32 v91, v91, v92
	v_add_u32_e32 v92, s62, v144
	v_ashrrev_i32_e32 v93, 31, v92
	v_lshlrev_b64 v[92:93], 12, v[92:93]
	v_lshl_add_u64 v[92:93], v[132:133], 0, v[92:93]
	global_store_dwordx2 v[164:165], v[90:91], off offset:32
	v_lshl_add_u64 v[92:93], v[92:93], 0, s[4:5]
	v_lshl_add_u64 v[90:91], s[40:41], 0, v[0:1]
	global_load_dword v0, v0, s[40:41] offset:64
	s_waitcnt vmcnt(0)
	v_add_f32_e32 v86, v86, v0
	global_load_dwordx2 v[164:165], v[92:93], off
	v_add_f32_e32 v87, v87, v0
	v_add_f32_e32 v88, v88, v0
	v_add_f32_e32 v89, v89, v0
	v_add_f32_e32 v82, v82, v0
	v_add_f32_e32 v83, v83, v0
	v_add_f32_e32 v84, v84, v0
	v_add_f32_e32 v0, v85, v0
	s_waitcnt vmcnt(0)
	v_lshlrev_b32_e32 v156, 16, v164
	v_mul_f32_e32 v86, v86, v156
	v_and_b32_e32 v156, 0xffff0000, v164
	v_mul_f32_e32 v87, v87, v156
	v_cvt_pk_bf16_f32 v86, v86, v87
	v_lshlrev_b32_e32 v87, 16, v165
	v_mul_f32_e32 v87, v88, v87
	v_and_b32_e32 v88, 0xffff0000, v165
	v_mul_f32_e32 v88, v89, v88
	v_cvt_pk_bf16_f32 v87, v87, v88
	global_store_dwordx2 v[92:93], v[86:87], off
	global_load_dwordx2 v[86:87], v[92:93], off offset:32
	s_waitcnt vmcnt(0)
	v_lshlrev_b32_e32 v88, 16, v86
	v_and_b32_e32 v86, 0xffff0000, v86
	v_mul_f32_e32 v82, v82, v88
	v_mul_f32_e32 v83, v83, v86
	v_cvt_pk_bf16_f32 v82, v82, v83
	v_lshlrev_b32_e32 v83, 16, v87
	v_mul_f32_e32 v83, v84, v83
	v_and_b32_e32 v84, 0xffff0000, v87
	v_mul_f32_e32 v0, v0, v84
	v_cvt_pk_bf16_f32 v83, v83, v0
	global_store_dwordx2 v[92:93], v[82:83], off offset:32
	s_and_saveexec_b64 s[4:5], vcc
	s_cbranch_execz .LBB0_1593
; __device__ __forceinline__ unsigned cvt_pk(float lo, float hi) { unsigned r; asm("v_cvt_pk_bf16_f32 %0, %1, %2" : "=v"(r) : "v"(lo), "v"(hi)); return r; }
; __device__ __forceinline__ float bflo(unsigned w) { return __uint_as_float(w << 16); }
; __device__ __forceinline__ float bfhi(unsigned w) { return __uint_as_float(w & 0xffff0000u); }
; __device__ __forceinline__ void spatial_phase(unsigned char* lds, const Params& p, int vb, int G, bool dry) {
;     ...
;         for (int tb = 0; tb < 8; ++tb) { const int t = 16 * tb + li;
;             if (t < L && !dry) { const float bs = p.in[16][g * 128 + t];
; #pragma unroll
;                 for (int v = 0; v < 2; ++v) { bf16_t* up = U + (size_t)(row0 + t) * D + g * 256 + 16 * (2 * wave + v) + 4 * fq; const u32x2 uw = *(const u32x2*)up;
;                     u32x2 w; w.x = cvt_pk(bflo(uw.x) * (acc[v][tb][0] + bs), bfhi(uw.x) * (acc[v][tb][1] + bs)); w.y = cvt_pk(bflo(uw.y) * (acc[v][tb][2] + bs), bfhi(uw.y) * (acc[v][tb][3] + bs)); *(u32x2*)up = w; } } }
	v_add_u32_e32 v82, s62, v145
	v_ashrrev_i32_e32 v83, 31, v82
	v_lshlrev_b64 v[82:83], 12, v[82:83]
	v_lshl_add_u64 v[82:83], v[132:133], 0, v[82:83]
	v_lshl_add_u64 v[82:83], s[38:39], 1, v[82:83]
	global_load_dword v0, v[90:91], off offset:128
	global_load_dwordx2 v[84:85], v[82:83], off
	s_waitcnt vmcnt(1)
	v_add_f32_e32 v78, v78, v0
	s_waitcnt vmcnt(0)
	v_lshlrev_b32_e32 v86, 16, v84
	v_and_b32_e32 v84, 0xffff0000, v84
	v_add_f32_e32 v79, v79, v0
	v_mul_f32_e32 v78, v78, v86
	v_mul_f32_e32 v79, v79, v84
	v_cvt_pk_bf16_f32 v78, v78, v79
	v_lshlrev_b32_e32 v79, 16, v85
	v_add_f32_e32 v80, v80, v0
	v_mul_f32_e32 v79, v80, v79
	v_and_b32_e32 v80, 0xffff0000, v85
	v_add_f32_e32 v81, v81, v0
	v_mul_f32_e32 v80, v81, v80
	v_cvt_pk_bf16_f32 v79, v79, v80
	global_store_dwordx2 v[82:83], v[78:79], off
	global_load_dwordx2 v[78:79], v[82:83], off offset:32
	v_add_f32_e32 v74, v74, v0
	v_add_f32_e32 v75, v75, v0
	v_add_f32_e32 v76, v76, v0
	v_add_f32_e32 v0, v77, v0
	s_waitcnt vmcnt(0)
	v_lshlrev_b32_e32 v80, 16, v78
	v_and_b32_e32 v78, 0xffff0000, v78
	v_mul_f32_e32 v74, v74, v80
	v_mul_f32_e32 v75, v75, v78
	v_cvt_pk_bf16_f32 v74, v74, v75
	v_lshlrev_b32_e32 v75, 16, v79
	v_mul_f32_e32 v75, v76, v75
	v_and_b32_e32 v76, 0xffff0000, v79
	v_mul_f32_e32 v0, v0, v76
	v_cvt_pk_bf16_f32 v75, v75, v0
	global_store_dwordx2 v[82:83], v[74:75], off offset:32
	s_or_b64 exec, exec, s[4:5]
	v_cmp_gt_u32_e32 vcc, s63, v146
	s_and_saveexec_b64 s[4:5], vcc
	s_cbranch_execnz .LBB0_1594
